# v77 + waves 0-3 at priority 1 through the GDN chunk-local unit loop; GEMM tile restart: leading half at priority 1 until its first MFMA block
# baseline (speedup 1.0000x reference)
; #define LAS __attribute__((address_space(3)))
; #define PG8_BAR __builtin_amdgcn_s_barrier()
; __device__ __forceinline__ void gemm_phase(LAS unsigned char* lds, const Gemm g, const StaticOrder& S, const LAS Epi* Ep, const int tid) {
;     ...
;         if (wr == 0) PG8_BAR;
;         { const Epi E = load_epi(Ep); E(acc, cur, wr, wc, fr, fq, (LAS f32x4*)(lds + 135168 + (wid * 64 + lane) * 32), cur.pm == rs_pm); rs_pm = cur.pm; }
;         if (!has_next) break;
; #pragma unroll
;         for (int a = 0; a < 2; ++a)
; #pragma unroll
;             for (int b = 0; b < 2; ++b)
; #pragma unroll
;                 for (int m = 0; m < 4; ++m)
; #pragma unroll
;                     for (int n = 0; n < 2; ++n) acc[a][b][m][n] = (f32x4){0.f, 0.f, 0.f, 0.f};
;         cur = nxt; cA = nA; cB = nB; ++ui;
;         if (wr == 1) PG8_BAR;
.LBB0_642:
	s_and_b64 vcc, exec, s[46:47]
	s_mov_b64 s[0:1], -1
	s_cbranch_vccnz .LBB0_399
	s_mov_b32 s32, 0
	s_setprio 1
	s_andn2_b64 vcc, exec, s[6:7]
	s_cbranch_vccnz .LBB0_398
	s_setprio 0
	s_mov_b32 s32, 1
	s_branch .LBB0_398

; #define LAS __attribute__((address_space(3)))
; __device__ __forceinline__ void lds_barrier() { asm volatile("s_waitcnt lgkmcnt(0)" ::: "memory"); __builtin_amdgcn_s_barrier(); asm volatile("" ::: "memory"); }
; __device__ __forceinline__ LAS unsigned char* vbase(LAS unsigned char* p) { unsigned v = (unsigned)(uintptr_t)p; asm volatile("" : "+v"(v)); return (LAS unsigned char*)(uintptr_t)v; }
; __device__ __forceinline__ void gdn_local_unit(LAS unsigned char* lds, const GdnP& P, int unit, const int tid, const int pf) {
;     const int w = __builtin_amdgcn_readfirstlane(tid >> 6), lane = tid & 63, l15 = lane & 15, quad = lane >> 4;
;     const int h = unit & 7, cn = unit >> 3, n = cn & 63, row0 = cn * 64;
;     LAS float* Qs = (LAS float*)vbase(lds + GL_Q); LAS float* Ks = (LAS float*)vbase(lds + GL_K); LAS float* Vs = (LAS float*)vbase(lds + GL_V); LAS float* Ms = (LAS float*)vbase(lds + GL_M);
;     LAS float* rq = (LAS float*)vbase(lds + GL_SM); LAS float* rk = rq + 64; LAS float* beta = rq + 128; LAS float* Gc = rq + 192; LAS float* eG = rq + 256; LAS float* gb = rq + 320;
;     lds_barrier();
;     if (tid < 384 && !(pf & 32)) {
;         const int c8 = tid & 15, which = (tid >> 4) % 3, tseg = tid / 48, t0 = tseg * 8, col = which * 1024 + h * 128 + c8 * 8;
; __global__ void __launch_bounds__(NTHREADS, 2) mega(Args a) {
;     ...
;     if (lo <= P_GDNL && P_GDNL < hi) {
;         PHASE_HEAD
;         GdnP GP{proj, (const bf16_t*)(ws + WS_HALO), (const float*)(ws + WS_BAF), AIN(I_CONV), AIN(I_ALOG), AIN(I_DTB), (bf16_t*)(ws + WS_WBUF), (bf16_t*)(ws + WS_ATTN), (float*)(ws + WS_CD), (float*)(ws + WS_RSTDO)};
;         for (int u = bx; u < 2048; u += G) gdn_local_unit(lds, GP, u, tid, a.probe);
.LBB0_747:
	s_cmp_lt_i32 s64, 5
	s_cselect_b64 s[48:49], -1, 0
	s_cmp_gt_i32 s65, 4
	s_cselect_b64 s[0:1], -1, 0
	s_and_b64 s[0:1], s[48:49], s[0:1]
	s_andn2_b64 vcc, exec, s[0:1]
	s_cbranch_vccnz .LBB0_1049
	v_readlane_b32 s0, v253, 0
	v_readlane_b32 s1, v253, 1
	s_load_dwordx2 s[0:1], s[0:1], 0xd8
	s_mov_b32 s50, 0
	s_ashr_i32 s51, s50, 31
	v_mov_b32_e32 v165, v205
	s_waitcnt lgkmcnt(0)
	s_add_u32 s56, s0, s50
	s_addc_u32 s57, s1, s51
	s_mov_b32 s59, 0
	s_cmpk_gt_i32 s66, 0x7ff
	v_readfirstlane_b32 s55, v165
	v_and_b32_e32 v103, 63, v165
	v_lshlrev_b32_e32 v164, 3, v165
	s_cbranch_scc1 .LBB0_1044
	s_add_u32 s68, s56, 0x9300000
	s_addc_u32 s69, s57, 0
	s_add_u32 s70, s56, 0x1a00000
	s_addc_u32 s71, s57, 0
	s_add_u32 s72, s56, 0x1e80000
	s_addc_u32 s73, s57, 0
	s_lshl_b64 s[0:1], s[50:51], 3
	v_readlane_b32 s2, v253, 0
	v_readlane_b32 s3, v253, 1
	s_add_u32 s0, s2, s0
	s_addc_u32 s1, s3, s1
	s_load_dwordx2 s[74:75], s[0:1], 0x50
	s_load_dwordx4 s[44:47], s[0:1], 0x40
	s_nop 0
	s_load_dword s2, s[2:3], 0xe8
	s_add_u32 s82, s56, 0xa2000
	s_addc_u32 s83, s57, 0
	s_movk_i32 s0, 0x180
	v_cmp_gt_i32_e32 vcc, s0, v165
	s_waitcnt lgkmcnt(0)
	s_bitcmp0_b32 s2, 5
	s_cselect_b64 s[0:1], -1, 0
	s_and_b64 s[76:77], vcc, s[0:1]
	v_ashrrev_i32_e32 v0, 4, v165
	s_mov_b32 s0, 0x55555556
	v_mul_hi_i32 v1, v0, s0
	v_lshrrev_b32_e32 v2, 31, v1
	v_add_u32_e32 v1, v1, v2
	v_lshl_add_u32 v1, v1, 1, v1
	s_mov_b32 s0, 0x2aaaaaab
	v_sub_u32_e32 v167, v0, v1
	v_mul_hi_i32 v0, v165, s0
	v_lshrrev_b32_e32 v1, 31, v0
	v_ashrrev_i32_e32 v0, 3, v0
	s_movk_i32 s0, 0xffd1
	v_add_u32_e32 v0, v0, v1
	v_cmp_gt_i32_e64 s[6:7], s0, v165
	s_movk_i32 s0, 0x1080
	v_mul_lo_u32 v172, v0, s0
	s_movk_i32 s0, 0x7f
	v_cmp_lt_i32_e64 s[8:9], s0, v165
	s_movk_i32 s0, 0xc0
	v_cmp_gt_u32_e64 s[10:11], s0, v165
	s_movk_i32 s0, 0x800
	v_cmp_gt_i32_e64 s[28:29], s0, v165
	s_add_i32 s0, 0, 0x21400
	v_and_b32_e32 v191, 48, v165
	s_bitcmp1_b32 s2, 1
	s_movk_i32 s2, 0xff
	v_add_u32_e32 v1, s0, v191
	s_cselect_b64 s[0:1], -1, 0
	v_cmp_lt_i32_e64 s[30:31], s2, v165
	v_and_b32_e32 v166, 15, v165
	s_or_b64 s[78:79], s[30:31], s[0:1]
	s_movk_i32 s0, 0x500
	v_mov_b32_e32 v101, 0
	v_lshlrev_b32_e32 v98, 4, v166
	v_cmp_gt_u32_e64 s[34:35], s0, v165
	v_lshlrev_b32_e32 v198, 1, v165
	s_add_i32 s0, 0, 0x1d000
	v_mov_b32_e32 v99, v101
	v_add_u32_e32 v199, s0, v198
	v_add_u32_e32 v102, s0, v98
	v_lshl_add_u64 v[2:3], s[56:57], 0, v[98:99]
	s_mov_b64 s[0:1], 0x6600000
	v_lshlrev_b32_e32 v100, 1, v166
	v_lshl_add_u64 v[104:105], v[2:3], 0, s[0:1]
	v_lshl_add_u64 v[2:3], s[56:57], 0, v[100:101]
	s_mov_b64 s[0:1], 0x1fb00000
	v_lshl_add_u64 v[106:107], v[2:3], 0, s[0:1]
	s_add_i32 s0, 0, 0x8400
	v_lshlrev_b32_e32 v76, 3, v0
	v_mov_b32_e32 v208, s0
	s_add_i32 s0, 0, 0x10800
	v_or_b32_e32 v78, 1, v76
	v_lshlrev_b32_e32 v173, 12, v0
	s_movk_i32 s84, 0x210
	v_lshrrev_b32_e32 v0, 2, v165
	v_add_u32_e32 v5, 0xffffff00, v165
	v_mov_b32_e32 v209, s0
	s_add_i32 s0, 0, 0x18800
	v_and_b32_e32 v168, 0x78, v164
	v_or_b32_e32 v80, 2, v76
	v_or_b32_e32 v82, 3, v76
	v_or_b32_e32 v84, 4, v76
	v_or_b32_e32 v86, 5, v76
	v_or_b32_e32 v88, 6, v76
	v_or_b32_e32 v90, 7, v76
	v_add_u32_e32 v92, 8, v76
	v_add_u32_e32 v94, 9, v76
	v_add_u32_e32 v96, 10, v76
	v_mul_lo_u32 v174, v78, s84
	v_and_b32_e32 v192, 12, v0
	v_mul_u32_u24_e32 v4, 0x110, v166
	s_movk_i32 s85, 0x400
	v_lshlrev_b32_e32 v0, 3, v166
	v_lshrrev_b32_e32 v203, 4, v5
	v_mov_b32_e32 v2, 0xffffc000
	v_mov_b32_e32 v210, s0
	s_add_i32 s0, 0, 0x1c800
	v_cmp_gt_i32_e64 s[4:5], 48, v165
	v_ashrrev_i32_e32 v77, 31, v76
	v_add_u32_e32 v169, -3, v76
	v_ashrrev_i32_e32 v79, 31, v78
	v_add_u32_e32 v170, -2, v76
	v_ashrrev_i32_e32 v81, 31, v80
	v_add_u32_e32 v171, -1, v76
	v_ashrrev_i32_e32 v83, 31, v82
	v_ashrrev_i32_e32 v85, 31, v84
	v_ashrrev_i32_e32 v87, 31, v86
	v_ashrrev_i32_e32 v89, 31, v88
	v_ashrrev_i32_e32 v91, 31, v90
	v_ashrrev_i32_e32 v93, 31, v92
	v_ashrrev_i32_e32 v95, 31, v94
	v_ashrrev_i32_e32 v97, 31, v96
	v_lshlrev_b32_e32 v175, 9, v78
	v_add_u32_e32 v176, 0x210, v174
	v_lshlrev_b32_e32 v177, 9, v80
	v_add_u32_e32 v178, 0x420, v174
	v_lshlrev_b32_e32 v179, 9, v82
	v_add_u32_e32 v180, 0x630, v174
	v_lshlrev_b32_e32 v181, 9, v84
	v_add_u32_e32 v182, 0x840, v174
	v_lshlrev_b32_e32 v183, 9, v86
	v_add_u32_e32 v184, 0xa50, v174
	v_lshlrev_b32_e32 v185, 9, v88
	v_add_u32_e32 v186, 0xc60, v174
	v_lshlrev_b32_e32 v187, 9, v90
	v_add_u32_e32 v188, 0xffffff80, v165
	v_cmp_gt_i32_e64 s[12:13], 64, v165
	v_cmp_lt_i32_e64 s[14:15], 63, v165
	v_mul_u32_u24_e32 v189, 0x210, v103
	v_cmp_eq_u32_e64 s[16:17], 0, v103
	v_cmp_gt_u32_e64 s[18:19], 2, v103
	v_cmp_gt_u32_e64 s[20:21], 4, v103
	v_cmp_gt_u32_e64 s[22:23], 8, v103
	v_cmp_gt_u32_e64 s[24:25], 16, v103
	v_cmp_gt_u32_e64 s[26:27], 32, v103
	v_lshlrev_b32_e32 v190, 5, v166
	v_or_b32_e32 v193, 16, v166
	v_or_b32_e32 v194, 32, v166
	v_or_b32_e32 v195, 48, v166
	v_and_b32_e32 v196, 0x7f, v165
	v_bfe_u32 v197, v165, 1, 6
	v_cmp_eq_u32_e64 s[36:37], 0, v5
	v_add_u32_e32 v200, 0xffffff00, v199
	v_cmp_gt_i32_e64 s[38:39], s85, v165
	v_lshl_or_b32 v99, v167, 10, v168
	v_add_u32_e32 v201, 0xfffffe00, v165
	v_add_u32_e32 v202, 0xfffff800, v164
	v_mul_lo_u32 v204, v203, s84
	v_lshlrev_b32_e32 v206, 2, v203
	v_lshl_add_u32 v207, v165, 6, v2
	v_mov_b32_e32 v211, s0
	s_movk_i32 s86, 0x1800
	s_movk_i32 s87, 0x5a00
	s_mov_b32 s88, 0x3fb8aa3b
	s_mov_b32 s89, 0xc2ce8ed0
	s_mov_b32 s90, 0x42b17218
	v_mov_b32_e32 v212, 0x3ecc95a3
	v_mov_b32_e32 v213, 0x260
	s_movk_i32 s91, 0x2ff
	v_lshlrev_b32_e32 v108, 1, v0
	v_mov_b32_e32 v214, 0x7f800000
	v_mov_b32_e32 v110, 0x3f317218
	v_mbcnt_hi_u32_b32 v215, -1, v226
	v_mov_b32_e32 v216, 0x21400
	v_mov_b32_e32 v217, 0x1d000
	v_add_u32_e32 v218, v1, v4
	s_mov_b32 s80, s66
	v_readfirstlane_b32 s32, v165
	s_cmpk_lt_u32 s32, 0x100
	s_cbranch_scc0 .Lgprio_skip
	s_setprio 1
.Lgprio_skip:
	s_branch .LBB0_751
.LBB0_750:
	s_or_b64 exec, exec, s[0:1]
	v_readlane_b32 s0, v253, 16
	s_add_i32 s80, s80, s0
	s_cmpk_gt_i32 s80, 0x7ff
	s_cbranch_scc1 .LBB0_1044

; __device__ __forceinline__ unsigned xb_add(unsigned* p, unsigned v) { return __hip_atomic_fetch_add(p, v, __ATOMIC_RELAXED, __HIP_MEMORY_SCOPE_AGENT); }
; __device__ __forceinline__ void xcd_barrier(const XcdBarrier& b) {
;     asm volatile("s_waitcnt vmcnt(0)" ::: "memory");
;     __syncthreads();
;     if (threadIdx.x == 0) {
;         unsigned* bar = b.bar;
;         __builtin_amdgcn_s_waitcnt(0);
;         unsigned nloc = b.st[0], nx = b.st[1];
;         if (nloc == 0u) { xcd_barrier_complete(bar, b.x, nloc, nx); b.st[0] = nloc; b.st[1] = nx; }
;         const unsigned old = xb_add(&bar[XB_XSUB(b.x)], 1u);
.LBB0_1049:
	s_cmp_gt_i32 s65, 5
	s_cselect_b64 s[0:1], -1, 0
	s_and_b64 s[2:3], s[48:49], s[0:1]
	s_andn2_b64 vcc, exec, s[2:3]
	s_cbranch_vccnz .LBB0_1117
	s_cmpk_lt_u32 s65, 0x3e9
	s_mov_b64 s[4:5], -1
	s_cbranch_scc0 .LBB0_1104
	s_setprio 0
	s_waitcnt vmcnt(0)
	s_waitcnt lgkmcnt(0)
	s_barrier
	s_mov_b64 s[4:5], exec
	v_readlane_b32 s2, v253, 9
	v_readlane_b32 s3, v253, 10
	s_and_b64 s[2:3], s[4:5], s[2:3]
	s_mov_b64 exec, s[2:3]
	s_cbranch_execz .LBB0_1103
	s_add_i32 s2, 0, 0x27500
	v_mov_b32_e32 v0, s2
	s_waitcnt vmcnt(0) expcnt(0) lgkmcnt(0)
	ds_read_b32 v2, v0
	s_add_i32 s2, 0, 0x27504
	v_mov_b32_e32 v0, s2
	ds_read_b32 v0, v0
	s_waitcnt lgkmcnt(1)
	v_cmp_ne_u32_e32 vcc, 0, v2
	s_cbranch_vccnz .LBB0_1067
	v_readlane_b32 s6, v253, 2
	v_readlane_b32 s7, v253, 3
	v_readlane_b32 s12, v253, 6
	s_load_dwordx2 s[2:3], s[6:7], 0x4
	v_readlane_b32 s13, v253, 7
	s_add_u32 s6, s12, 0x1000
	s_addc_u32 s7, s13, 0
	s_add_u32 s8, s12, 0x1100
	s_addc_u32 s9, s13, 0
	s_add_u32 s10, s12, 0x1200
	s_addc_u32 s11, s13, 0
	s_waitcnt lgkmcnt(0)
	s_mul_i32 s2, s2, s69
	s_add_u32 s12, s12, 0x1300
	s_mul_i32 s2, s2, s3
	s_addc_u32 s13, s13, 0
	s_mov_b32 s3, 1
	v_mov_b32_e32 v16, 0
	s_branch .LBB0_1055

; #define LAS __attribute__((address_space(3)))
; #define PG8_BAR __builtin_amdgcn_s_barrier()
; __device__ __forceinline__ void gemm_phase(LAS unsigned char* lds, const Gemm g, const StaticOrder& S, const LAS Epi* Ep, const int tid) {
;     ...
;         if (wr == 0) PG8_BAR;
;         { const Epi E = load_epi(Ep); E(acc, cur, wr, wc, fr, fq, (LAS f32x4*)(lds + 135168 + (wid * 64 + lane) * 32), cur.pm == rs_pm); rs_pm = cur.pm; }
;         if (!has_next) break;
; #pragma unroll
;         for (int a = 0; a < 2; ++a)
; #pragma unroll
;             for (int b = 0; b < 2; ++b)
; #pragma unroll
;                 for (int m = 0; m < 4; ++m)
; #pragma unroll
;                     for (int n = 0; n < 2; ++n) acc[a][b][m][n] = (f32x4){0.f, 0.f, 0.f, 0.f};
;         cur = nxt; cA = nA; cB = nB; ++ui;
;         if (wr == 1) PG8_BAR;
.LBB0_1631:
	s_and_b64 vcc, exec, s[46:47]
	s_mov_b64 s[0:1], -1
	s_cbranch_vccnz .LBB0_1426
	s_mov_b32 s32, 0
	s_setprio 1
	s_andn2_b64 vcc, exec, s[28:29]
	s_cbranch_vccnz .LBB0_1425
	s_setprio 0
	s_mov_b32 s32, 1
	s_branch .LBB0_1425

; #define LAS __attribute__((address_space(3)))
; #define PG8_BAR __builtin_amdgcn_s_barrier()
; __device__ __forceinline__ void gemm_phase(LAS unsigned char* lds, const Gemm g, const StaticOrder& S, const LAS Epi* Ep, const int tid) {
;     ...
;         if (wr == 0) PG8_BAR;
;         { const Epi E = load_epi(Ep); E(acc, cur, wr, wc, fr, fq, (LAS f32x4*)(lds + 135168 + (wid * 64 + lane) * 32), cur.pm == rs_pm); rs_pm = cur.pm; }
;         if (!has_next) break;
; #pragma unroll
;         for (int a = 0; a < 2; ++a)
; #pragma unroll
;             for (int b = 0; b < 2; ++b)
; #pragma unroll
;                 for (int m = 0; m < 4; ++m)
; #pragma unroll
;                     for (int n = 0; n < 2; ++n) acc[a][b][m][n] = (f32x4){0.f, 0.f, 0.f, 0.f};
;         cur = nxt; cA = nA; cB = nB; ++ui;
;         if (wr == 1) PG8_BAR;
.LBB0_2081:
	s_and_b64 vcc, exec, s[46:47]
	s_mov_b64 s[0:1], -1
	s_cbranch_vccnz .LBB0_1838
	s_mov_b32 s32, 0
	s_setprio 1
	s_andn2_b64 vcc, exec, s[96:97]
	s_cbranch_vccnz .LBB0_1837
	s_setprio 0
	s_mov_b32 s32, 1
	s_branch .LBB0_1837
